# GEMM unit start: accumulator zeroing with 64x v_mov_b64 instead of 128x v_mov_b32 (6 GEMM instances)
# speedup vs baseline: 1.0040x; 1.0020x over previous
.LBB0_209:
	s_ashr_i32 s11, s10, 31
	s_lshl_b64 s[18:19], s[10:11], 19
	s_add_u32 s18, s40, s18
	s_addc_u32 s19, s41, s19
	s_and_b64 s[24:25], s[44:45], exec
	s_cselect_b32 s11, s19, s21
	s_cselect_b32 s59, s18, s20
	s_ashr_i32 s15, s14, 31
	s_lshl_b64 s[24:25], s[14:15], 19
	s_add_u32 s36, s34, s24
	s_addc_u32 s37, s35, s25
	s_and_b64 s[24:25], s[44:45], exec
	s_cselect_b32 s15, s37, s23
	s_cselect_b32 s60, s36, s22
	s_add_u32 s20, s20, 0x40080
	s_addc_u32 s21, s21, 0
	s_add_u32 s61, s22, 0x100
	s_addc_u32 s64, s23, 0
	s_mov_b32 s65, -2
	v_mov_b64_e32 v[2:3], 0
	v_mov_b64_e32 v[4:5], 0
	v_mov_b64_e32 v[6:7], 0
	v_mov_b64_e32 v[8:9], 0
	v_mov_b64_e32 v[10:11], 0
	v_mov_b64_e32 v[12:13], 0
	v_mov_b64_e32 v[14:15], 0
	v_mov_b64_e32 v[16:17], 0
	v_mov_b64_e32 v[18:19], 0
	v_mov_b64_e32 v[20:21], 0
	v_mov_b64_e32 v[22:23], 0
	v_mov_b64_e32 v[24:25], 0
	v_mov_b64_e32 v[26:27], 0
	v_mov_b64_e32 v[28:29], 0
	v_mov_b64_e32 v[30:31], 0
	v_mov_b64_e32 v[32:33], 0
	v_mov_b64_e32 v[34:35], 0
	v_mov_b64_e32 v[36:37], 0
	v_mov_b64_e32 v[38:39], 0
	v_mov_b64_e32 v[40:41], 0
	v_mov_b64_e32 v[42:43], 0
	v_mov_b64_e32 v[44:45], 0
	v_mov_b64_e32 v[46:47], 0
	v_mov_b64_e32 v[48:49], 0
	v_mov_b64_e32 v[50:51], 0
	v_mov_b64_e32 v[52:53], 0
	v_mov_b64_e32 v[54:55], 0
	v_mov_b64_e32 v[56:57], 0
	v_mov_b64_e32 v[58:59], 0
	v_mov_b64_e32 v[60:61], 0
	v_mov_b64_e32 v[62:63], 0
	v_mov_b64_e32 v[64:65], 0
	v_mov_b64_e32 v[66:67], 0
	v_mov_b64_e32 v[68:69], 0
	v_mov_b64_e32 v[70:71], 0
	v_mov_b64_e32 v[72:73], 0
	v_mov_b64_e32 v[74:75], 0
	v_mov_b64_e32 v[76:77], 0
	v_mov_b64_e32 v[78:79], 0
	v_mov_b64_e32 v[80:81], 0
	v_mov_b64_e32 v[82:83], 0
	v_mov_b64_e32 v[84:85], 0
	v_mov_b64_e32 v[86:87], 0
	v_mov_b64_e32 v[88:89], 0
	v_mov_b64_e32 v[90:91], 0
	v_mov_b64_e32 v[92:93], 0
	v_mov_b64_e32 v[94:95], 0
	v_mov_b64_e32 v[96:97], 0
	v_mov_b64_e32 v[98:99], 0
	v_mov_b64_e32 v[100:101], 0
	v_mov_b64_e32 v[102:103], 0
	v_mov_b64_e32 v[104:105], 0
	v_mov_b64_e32 v[106:107], 0
	v_mov_b64_e32 v[108:109], 0
	v_mov_b64_e32 v[110:111], 0
	v_mov_b64_e32 v[112:113], 0
	v_mov_b64_e32 v[114:115], 0
	v_mov_b64_e32 v[116:117], 0
	v_mov_b64_e32 v[118:119], 0
	v_mov_b64_e32 v[120:121], 0
	v_mov_b64_e32 v[122:123], 0
	v_mov_b64_e32 v[124:125], 0
	v_mov_b64_e32 v[126:127], 0
	v_mov_b64_e32 v[128:129], 0

.LBB0_283:
	s_add_u32 s48, s20, 0x100
	s_addc_u32 s49, s21, 0
	s_mov_b32 s65, -2
	v_mov_b64_e32 v[2:3], 0
	v_mov_b64_e32 v[4:5], 0
	v_mov_b64_e32 v[6:7], 0
	v_mov_b64_e32 v[8:9], 0
	v_mov_b64_e32 v[10:11], 0
	v_mov_b64_e32 v[12:13], 0
	v_mov_b64_e32 v[14:15], 0
	v_mov_b64_e32 v[16:17], 0
	v_mov_b64_e32 v[18:19], 0
	v_mov_b64_e32 v[20:21], 0
	v_mov_b64_e32 v[22:23], 0
	v_mov_b64_e32 v[24:25], 0
	v_mov_b64_e32 v[26:27], 0
	v_mov_b64_e32 v[28:29], 0
	v_mov_b64_e32 v[30:31], 0
	v_mov_b64_e32 v[32:33], 0
	v_mov_b64_e32 v[34:35], 0
	v_mov_b64_e32 v[36:37], 0
	v_mov_b64_e32 v[38:39], 0
	v_mov_b64_e32 v[40:41], 0
	v_mov_b64_e32 v[42:43], 0
	v_mov_b64_e32 v[44:45], 0
	v_mov_b64_e32 v[46:47], 0
	v_mov_b64_e32 v[48:49], 0
	v_mov_b64_e32 v[50:51], 0
	v_mov_b64_e32 v[52:53], 0
	v_mov_b64_e32 v[54:55], 0
	v_mov_b64_e32 v[56:57], 0
	v_mov_b64_e32 v[58:59], 0
	v_mov_b64_e32 v[60:61], 0
	v_mov_b64_e32 v[62:63], 0
	v_mov_b64_e32 v[64:65], 0
	v_mov_b64_e32 v[66:67], 0
	v_mov_b64_e32 v[68:69], 0
	v_mov_b64_e32 v[70:71], 0
	v_mov_b64_e32 v[72:73], 0
	v_mov_b64_e32 v[74:75], 0
	v_mov_b64_e32 v[76:77], 0
	v_mov_b64_e32 v[78:79], 0
	v_mov_b64_e32 v[80:81], 0
	v_mov_b64_e32 v[82:83], 0
	v_mov_b64_e32 v[84:85], 0
	v_mov_b64_e32 v[86:87], 0
	v_mov_b64_e32 v[88:89], 0
	v_mov_b64_e32 v[90:91], 0
	v_mov_b64_e32 v[92:93], 0
	v_mov_b64_e32 v[94:95], 0
	v_mov_b64_e32 v[96:97], 0
	v_mov_b64_e32 v[98:99], 0
	v_mov_b64_e32 v[100:101], 0
	v_mov_b64_e32 v[102:103], 0
	v_mov_b64_e32 v[104:105], 0
	v_mov_b64_e32 v[106:107], 0
	v_mov_b64_e32 v[108:109], 0
	v_mov_b64_e32 v[110:111], 0
	v_mov_b64_e32 v[112:113], 0
	v_mov_b64_e32 v[114:115], 0
	v_mov_b64_e32 v[116:117], 0
	v_mov_b64_e32 v[118:119], 0
	v_mov_b64_e32 v[120:121], 0
	v_mov_b64_e32 v[122:123], 0
	v_mov_b64_e32 v[124:125], 0
	v_mov_b64_e32 v[126:127], 0
	v_mov_b64_e32 v[128:129], 0

.LBB0_417:
	s_ashr_i32 s1, s0, 31
	s_lshl_b64 s[14:15], s[0:1], 19
	s_add_u32 s14, s34, s14
	s_addc_u32 s15, s35, s15
	s_and_b64 s[18:19], s[46:47], exec
	s_cselect_b32 s1, s15, s21
	s_cselect_b32 s57, s14, s20
	s_ashr_i32 s11, s10, 31
	s_lshl_b64 s[18:19], s[10:11], 19
	s_add_u32 s18, s36, s18
	s_addc_u32 s19, s37, s19
	s_and_b64 s[24:25], s[46:47], exec
	s_cselect_b32 s11, s19, s23
	s_cselect_b32 s58, s18, s22
	s_add_u32 s20, s20, 0x40080
	s_addc_u32 s21, s21, 0
	s_add_u32 s59, s22, 0x100
	s_addc_u32 s60, s23, 0
	s_mov_b32 s61, -2
	v_mov_b64_e32 v[2:3], 0
	v_mov_b64_e32 v[4:5], 0
	v_mov_b64_e32 v[6:7], 0
	v_mov_b64_e32 v[8:9], 0
	v_mov_b64_e32 v[10:11], 0
	v_mov_b64_e32 v[12:13], 0
	v_mov_b64_e32 v[14:15], 0
	v_mov_b64_e32 v[16:17], 0
	v_mov_b64_e32 v[18:19], 0
	v_mov_b64_e32 v[20:21], 0
	v_mov_b64_e32 v[22:23], 0
	v_mov_b64_e32 v[24:25], 0
	v_mov_b64_e32 v[26:27], 0
	v_mov_b64_e32 v[28:29], 0
	v_mov_b64_e32 v[30:31], 0
	v_mov_b64_e32 v[32:33], 0
	v_mov_b64_e32 v[34:35], 0
	v_mov_b64_e32 v[36:37], 0
	v_mov_b64_e32 v[38:39], 0
	v_mov_b64_e32 v[40:41], 0
	v_mov_b64_e32 v[42:43], 0
	v_mov_b64_e32 v[44:45], 0
	v_mov_b64_e32 v[46:47], 0
	v_mov_b64_e32 v[48:49], 0
	v_mov_b64_e32 v[50:51], 0
	v_mov_b64_e32 v[52:53], 0
	v_mov_b64_e32 v[54:55], 0
	v_mov_b64_e32 v[56:57], 0
	v_mov_b64_e32 v[58:59], 0
	v_mov_b64_e32 v[60:61], 0
	v_mov_b64_e32 v[62:63], 0
	v_mov_b64_e32 v[64:65], 0
	v_mov_b64_e32 v[66:67], 0
	v_mov_b64_e32 v[68:69], 0
	v_mov_b64_e32 v[70:71], 0
	v_mov_b64_e32 v[72:73], 0
	v_mov_b64_e32 v[74:75], 0
	v_mov_b64_e32 v[76:77], 0
	v_mov_b64_e32 v[78:79], 0
	v_mov_b64_e32 v[80:81], 0
	v_mov_b64_e32 v[82:83], 0
	v_mov_b64_e32 v[84:85], 0
	v_mov_b64_e32 v[86:87], 0
	v_mov_b64_e32 v[88:89], 0
	v_mov_b64_e32 v[90:91], 0
	v_mov_b64_e32 v[92:93], 0
	v_mov_b64_e32 v[94:95], 0
	v_mov_b64_e32 v[96:97], 0
	v_mov_b64_e32 v[98:99], 0
	v_mov_b64_e32 v[100:101], 0
	v_mov_b64_e32 v[102:103], 0
	v_mov_b64_e32 v[104:105], 0
	v_mov_b64_e32 v[106:107], 0
	v_mov_b64_e32 v[108:109], 0
	v_mov_b64_e32 v[110:111], 0
	v_mov_b64_e32 v[112:113], 0
	v_mov_b64_e32 v[114:115], 0
	v_mov_b64_e32 v[116:117], 0
	v_mov_b64_e32 v[118:119], 0
	v_mov_b64_e32 v[120:121], 0
	v_mov_b64_e32 v[122:123], 0
	v_mov_b64_e32 v[124:125], 0
	v_mov_b64_e32 v[126:127], 0
	v_mov_b64_e32 v[128:129], 0

.LBB0_809:
	s_ashr_i32 s1, s0, 31
	s_lshl_b64 s[14:15], s[0:1], 19
	s_add_u32 s14, s36, s14
	s_addc_u32 s15, s37, s15
	s_and_b64 s[18:19], s[44:45], exec
	s_cselect_b32 s1, s15, s21
	s_cselect_b32 s65, s14, s20
	s_ashr_i32 s11, s10, 31
	s_lshl_b64 s[18:19], s[10:11], 19
	s_add_u32 s18, s40, s18
	s_addc_u32 s19, s41, s19
	s_and_b64 s[24:25], s[44:45], exec
	s_cselect_b32 s11, s19, s23
	s_cselect_b32 s70, s18, s22
	s_add_u32 s76, s22, 0x100
	s_addc_u32 s77, s23, 0
	s_mov_b32 s87, -2
	v_mov_b64_e32 v[2:3], 0
	v_mov_b64_e32 v[4:5], 0
	v_mov_b64_e32 v[6:7], 0
	v_mov_b64_e32 v[8:9], 0
	v_mov_b64_e32 v[10:11], 0
	v_mov_b64_e32 v[12:13], 0
	v_mov_b64_e32 v[14:15], 0
	v_mov_b64_e32 v[16:17], 0
	v_mov_b64_e32 v[18:19], 0
	v_mov_b64_e32 v[20:21], 0
	v_mov_b64_e32 v[22:23], 0
	v_mov_b64_e32 v[24:25], 0
	v_mov_b64_e32 v[26:27], 0
	v_mov_b64_e32 v[28:29], 0
	v_mov_b64_e32 v[30:31], 0
	v_mov_b64_e32 v[32:33], 0
	v_mov_b64_e32 v[34:35], 0
	v_mov_b64_e32 v[36:37], 0
	v_mov_b64_e32 v[38:39], 0
	v_mov_b64_e32 v[40:41], 0
	v_mov_b64_e32 v[42:43], 0
	v_mov_b64_e32 v[44:45], 0
	v_mov_b64_e32 v[46:47], 0
	v_mov_b64_e32 v[48:49], 0
	v_mov_b64_e32 v[54:55], 0
	v_mov_b64_e32 v[56:57], 0
	v_mov_b64_e32 v[58:59], 0
	v_mov_b64_e32 v[60:61], 0
	v_mov_b64_e32 v[62:63], 0
	v_mov_b64_e32 v[64:65], 0
	v_mov_b64_e32 v[66:67], 0
	v_mov_b64_e32 v[68:69], 0
	v_mov_b64_e32 v[70:71], 0
	v_mov_b64_e32 v[72:73], 0
	v_mov_b64_e32 v[74:75], 0
	v_mov_b64_e32 v[76:77], 0
	v_mov_b64_e32 v[78:79], 0
	v_mov_b64_e32 v[80:81], 0
	v_mov_b64_e32 v[82:83], 0
	v_mov_b64_e32 v[84:85], 0
	v_mov_b64_e32 v[90:91], 0
	v_mov_b64_e32 v[92:93], 0
	v_mov_b64_e32 v[94:95], 0
	v_mov_b64_e32 v[96:97], 0
	v_mov_b64_e32 v[106:107], 0
	v_mov_b64_e32 v[108:109], 0
	v_mov_b64_e32 v[110:111], 0
	v_mov_b64_e32 v[112:113], 0
	v_mov_b64_e32 v[114:115], 0
	v_mov_b64_e32 v[116:117], 0
	v_mov_b64_e32 v[118:119], 0
	v_mov_b64_e32 v[120:121], 0
	v_mov_b64_e32 v[122:123], 0
	v_mov_b64_e32 v[124:125], 0
	v_mov_b64_e32 v[126:127], 0
	v_mov_b64_e32 v[128:129], 0
	v_mov_b64_e32 v[130:131], 0
	v_mov_b64_e32 v[132:133], 0
	v_mov_b64_e32 v[134:135], 0
	v_mov_b64_e32 v[136:137], 0
	v_mov_b64_e32 v[138:139], 0
	v_mov_b64_e32 v[140:141], 0
	v_mov_b64_e32 v[142:143], 0
	v_mov_b64_e32 v[144:145], 0

.LBB0_943:
	s_ashr_i32 s11, s10, 31
	s_lshl_b64 s[18:19], s[10:11], 19
	s_add_u32 s18, s34, s18
	s_addc_u32 s19, s35, s19
	s_and_b64 s[24:25], s[40:41], exec
	s_cselect_b32 s11, s19, s21
	s_cselect_b32 s59, s18, s20
	s_ashr_i32 s15, s14, 31
	s_lshl_b64 s[24:25], s[14:15], 19
	s_add_u32 s36, s42, s24
	s_addc_u32 s37, s43, s25
	s_and_b64 s[24:25], s[40:41], exec
	s_cselect_b32 s15, s37, s23
	s_cselect_b32 s60, s36, s22
	s_add_u32 s20, s20, 0x40080
	s_addc_u32 s21, s21, 0
	s_add_u32 s61, s22, 0x100
	s_addc_u32 s64, s23, 0
	s_mov_b32 s65, -2
	v_mov_b64_e32 v[2:3], 0
	v_mov_b64_e32 v[4:5], 0
	v_mov_b64_e32 v[6:7], 0
	v_mov_b64_e32 v[8:9], 0
	v_mov_b64_e32 v[10:11], 0
	v_mov_b64_e32 v[12:13], 0
	v_mov_b64_e32 v[14:15], 0
	v_mov_b64_e32 v[16:17], 0
	v_mov_b64_e32 v[18:19], 0
	v_mov_b64_e32 v[20:21], 0
	v_mov_b64_e32 v[22:23], 0
	v_mov_b64_e32 v[24:25], 0
	v_mov_b64_e32 v[26:27], 0
	v_mov_b64_e32 v[28:29], 0
	v_mov_b64_e32 v[30:31], 0
	v_mov_b64_e32 v[32:33], 0
	v_mov_b64_e32 v[34:35], 0
	v_mov_b64_e32 v[36:37], 0
	v_mov_b64_e32 v[38:39], 0
	v_mov_b64_e32 v[40:41], 0
	v_mov_b64_e32 v[42:43], 0
	v_mov_b64_e32 v[44:45], 0
	v_mov_b64_e32 v[46:47], 0
	v_mov_b64_e32 v[48:49], 0
	v_mov_b64_e32 v[50:51], 0
	v_mov_b64_e32 v[52:53], 0
	v_mov_b64_e32 v[54:55], 0
	v_mov_b64_e32 v[56:57], 0
	v_mov_b64_e32 v[58:59], 0
	v_mov_b64_e32 v[60:61], 0
	v_mov_b64_e32 v[62:63], 0
	v_mov_b64_e32 v[64:65], 0
	v_mov_b64_e32 v[66:67], 0
	v_mov_b64_e32 v[68:69], 0
	v_mov_b64_e32 v[70:71], 0
	v_mov_b64_e32 v[72:73], 0
	v_mov_b64_e32 v[74:75], 0
	v_mov_b64_e32 v[76:77], 0
	v_mov_b64_e32 v[78:79], 0
	v_mov_b64_e32 v[80:81], 0
	v_mov_b64_e32 v[82:83], 0
	v_mov_b64_e32 v[84:85], 0
	v_mov_b64_e32 v[86:87], 0
	v_mov_b64_e32 v[88:89], 0
	v_mov_b64_e32 v[90:91], 0
	v_mov_b64_e32 v[92:93], 0
	v_mov_b64_e32 v[94:95], 0
	v_mov_b64_e32 v[96:97], 0
	v_mov_b64_e32 v[98:99], 0
	v_mov_b64_e32 v[100:101], 0
	v_mov_b64_e32 v[102:103], 0
	v_mov_b64_e32 v[104:105], 0
	v_mov_b64_e32 v[106:107], 0
	v_mov_b64_e32 v[108:109], 0
	v_mov_b64_e32 v[110:111], 0
	v_mov_b64_e32 v[112:113], 0
	v_mov_b64_e32 v[114:115], 0
	v_mov_b64_e32 v[116:117], 0
	v_mov_b64_e32 v[118:119], 0
	v_mov_b64_e32 v[120:121], 0
	v_mov_b64_e32 v[122:123], 0
	v_mov_b64_e32 v[124:125], 0
	v_mov_b64_e32 v[126:127], 0
	v_mov_b64_e32 v[128:129], 0

.LBB0_1019:
	s_add_u32 s42, s18, 0x100
	s_addc_u32 s43, s19, 0
	s_mov_b32 s61, -2
	v_mov_b64_e32 v[2:3], 0
	v_mov_b64_e32 v[4:5], 0
	v_mov_b64_e32 v[6:7], 0
	v_mov_b64_e32 v[8:9], 0
	v_mov_b64_e32 v[10:11], 0
	v_mov_b64_e32 v[12:13], 0
	v_mov_b64_e32 v[14:15], 0
	v_mov_b64_e32 v[16:17], 0
	v_mov_b64_e32 v[18:19], 0
	v_mov_b64_e32 v[20:21], 0
	v_mov_b64_e32 v[22:23], 0
	v_mov_b64_e32 v[24:25], 0
	v_mov_b64_e32 v[26:27], 0
	v_mov_b64_e32 v[28:29], 0
	v_mov_b64_e32 v[30:31], 0
	v_mov_b64_e32 v[32:33], 0
	v_mov_b64_e32 v[34:35], 0
	v_mov_b64_e32 v[36:37], 0
	v_mov_b64_e32 v[38:39], 0
	v_mov_b64_e32 v[40:41], 0
	v_mov_b64_e32 v[42:43], 0
	v_mov_b64_e32 v[44:45], 0
	v_mov_b64_e32 v[46:47], 0
	v_mov_b64_e32 v[48:49], 0
	v_mov_b64_e32 v[50:51], 0
	v_mov_b64_e32 v[52:53], 0
	v_mov_b64_e32 v[54:55], 0
	v_mov_b64_e32 v[56:57], 0
	v_mov_b64_e32 v[58:59], 0
	v_mov_b64_e32 v[60:61], 0
	v_mov_b64_e32 v[62:63], 0
	v_mov_b64_e32 v[64:65], 0
	v_mov_b64_e32 v[66:67], 0
	v_mov_b64_e32 v[68:69], 0
	v_mov_b64_e32 v[70:71], 0
	v_mov_b64_e32 v[72:73], 0
	v_mov_b64_e32 v[74:75], 0
	v_mov_b64_e32 v[76:77], 0
	v_mov_b64_e32 v[78:79], 0
	v_mov_b64_e32 v[80:81], 0
	v_mov_b64_e32 v[82:83], 0
	v_mov_b64_e32 v[84:85], 0
	v_mov_b64_e32 v[86:87], 0
	v_mov_b64_e32 v[88:89], 0
	v_mov_b64_e32 v[90:91], 0
	v_mov_b64_e32 v[92:93], 0
	v_mov_b64_e32 v[94:95], 0
	v_mov_b64_e32 v[96:97], 0
	v_mov_b64_e32 v[98:99], 0
	v_mov_b64_e32 v[100:101], 0
	v_mov_b64_e32 v[102:103], 0
	v_mov_b64_e32 v[104:105], 0
	v_mov_b64_e32 v[106:107], 0
	v_mov_b64_e32 v[108:109], 0
	v_mov_b64_e32 v[110:111], 0
	v_mov_b64_e32 v[112:113], 0
	v_mov_b64_e32 v[114:115], 0
	v_mov_b64_e32 v[116:117], 0
	v_mov_b64_e32 v[118:119], 0
	v_mov_b64_e32 v[120:121], 0
	v_mov_b64_e32 v[122:123], 0
	v_mov_b64_e32 v[124:125], 0
	v_mov_b64_e32 v[126:127], 0
	v_mov_b64_e32 v[128:129], 0
